# S5 phases: scan waves (0-3) run at priority 3, the weight-transpose waves beside them at 0
# speedup vs baseline: 1.0094x; 1.0094x over previous
.LBB0_319:
	v_readlane_b32 s4, v253, 3
	v_readlane_b32 s5, v253, 4
	s_andn2_b64 vcc, exec, s[4:5]
	v_mbcnt_lo_u32_b32 v0, -1, 0
	v_mbcnt_hi_u32_b32 v0, -1, v0
	s_cbranch_vccnz .LBB0_328
	s_setprio 3
	v_readlane_b32 s4, v253, 14
	v_readlane_b32 s5, v253, 15
	s_mov_b64 s[26:27], 0
	s_mov_b64 s[36:37], 0
	s_mov_b64 s[20:21], 0
	s_mov_b64 s[24:25], 0
	s_mov_b64 s[22:23], 0
	s_mov_b64 s[30:31], 0
	s_mov_b64 s[38:39], 0
	s_mov_b64 s[28:29], 0
	s_andn2_b64 vcc, exec, s[4:5]
	s_cbranch_vccnz .LBB0_328
	s_mov_b32 s43, s6
	s_mov_b64 s[62:63], s[8:9]
	s_mov_b32 s1, s67
	s_mov_b32 s33, s7
	v_readlane_b32 s4, v252, 33
	s_lshl_b64 s[40:41], s[0:1], 12
	v_readlane_b32 s7, v252, 36
	v_readlane_b32 s12, v252, 41
	v_readlane_b32 s5, v252, 34
	v_readlane_b32 s8, v252, 37
	v_readlane_b32 s9, v252, 38
	v_readlane_b32 s13, v252, 42
	s_mov_b32 s7, s33
	s_add_u32 s33, s12, s40
	s_addc_u32 s40, s13, s41
	s_lshl_b64 s[4:5], s[0:1], 15
	v_readlane_b32 s8, v252, 24
	v_readlane_b32 s10, v252, 39
	v_readlane_b32 s11, v252, 40
	v_readlane_b32 s9, v252, 25
	s_add_u32 s41, s8, s4
	s_mov_b32 s65, s67
	s_addc_u32 s42, s9, s5
	s_lshl_b64 s[4:5], s[64:65], 2
	v_readlane_b32 s10, v252, 22
	v_readlane_b32 s11, v252, 23
	s_add_u32 s4, s10, s4
	s_addc_u32 s5, s11, s5
	s_add_u32 s10, s7, s26
	s_addc_u32 s11, s79, s27
	s_add_u32 s12, s89, s36
	s_addc_u32 s13, s78, s37
	s_add_u32 s4, s4, s20
	s_addc_u32 s5, s5, s21
	s_add_u32 s20, s41, s24
	s_addc_u32 s21, s42, s25
	s_add_u32 s24, s33, s38
	s_addc_u32 s25, s40, s39
	s_lshl_b64 s[38:39], s[0:1], 18
	v_readlane_b32 s8, v252, 26
	v_readlane_b32 s17, v252, 46
	v_readlane_b32 s9, v252, 27
	s_add_u32 s1, s8, s38
	s_addc_u32 s17, s9, s39
	v_readlane_b32 s8, v252, 28
	v_readlane_b32 s9, v252, 29
	s_add_u32 s33, s8, s38
	v_ashrrev_i32_e32 v6, 4, v0
	s_addc_u32 s38, s9, s39
	s_add_u32 s30, s33, s30
	v_lshlrev_b32_e32 v4, 3, v6
	v_readlane_b32 s6, v252, 35
	v_and_b32_e32 v76, 31, v0
	s_addc_u32 s31, s38, s31
	v_ashrrev_i32_e32 v5, 31, v4
	s_add_u32 s22, s1, s22
	v_lshl_add_u64 v[82:83], v[4:5], 1, s[30:31]
	v_lshlrev_b32_e32 v4, 6, v76
	v_and_b32_e32 v5, 0xffffffe0, v0
	v_readlane_b32 s6, v253, 16
	s_movk_i32 s1, 0x90
	s_waitcnt lgkmcnt(0)
	v_ashrrev_i32_e32 v1, 5, v0
	v_and_b32_e32 v77, 15, v0
	v_add3_u32 v102, s6, v4, v5
	v_mov_b32_e32 v4, s6
	v_mul_lo_u32 v9, v0, s1
	s_movk_i32 s1, 0x110
	v_lshlrev_b32_e32 v78, 3, v1
	v_lshl_add_u32 v7, v1, 4, s6
	v_mad_u32_u24 v1, v77, s1, v4
	v_and_b32_e32 v4, -16, v0
	v_add_u32_e32 v103, v1, v4
	s_movk_i32 s1, 0xfef4
	v_ashrrev_i32_e32 v4, 1, v0
	v_lshlrev_b32_e32 v5, 4, v0
	v_mad_i32_i24 v12, v77, s1, v1
	v_lshlrev_b32_e32 v1, 5, v4
	v_and_b32_e32 v5, 16, v5
	v_add3_u32 v104, s6, v1, v5
	v_ashrrev_i32_e32 v5, 31, v4
	v_lshlrev_b32_e32 v101, 1, v0
	v_lshlrev_b32_e32 v10, 2, v0
	v_lshlrev_b64 v[4:5], 11, v[4:5]
	v_and_b32_e32 v0, 1, v0
	v_ashrrev_i32_e32 v79, 31, v78
	v_lshl_add_u64 v[4:5], s[28:29], 0, v[4:5]
	v_lshlrev_b32_e32 v152, 4, v0
	s_addc_u32 s23, s17, s23
	v_lshlrev_b64 v[2:3], 1, v[78:79]
	v_lshl_add_u64 v[0:1], v[4:5], 0, v[152:153]
	v_lshlrev_b32_e32 v152, 11, v76
	v_readlane_b32 s1, v254, 39
	v_lshl_add_u64 v[80:81], s[22:23], 0, v[2:3]
	v_lshl_add_u64 v[84:85], s[86:87], 0, v[0:1]
	v_lshl_add_u64 v[0:1], s[26:27], 0, v[152:153]
	v_readlane_b32 s8, v254, 37
	s_add_u32 s22, s1, s36
	v_readlane_b32 s1, v254, 41
	v_lshl_add_u32 v8, v77, 1, s6
	v_lshlrev_b32_e32 v11, 8, v6
	v_lshlrev_b32_e32 v6, 7, v6
	v_mul_u32_u24_e32 v13, 0x90, v76
	v_lshl_add_u64 v[0:1], v[0:1], 0, v[2:3]
	v_readlane_b32 s9, v254, 38
	v_lshlrev_b32_e32 v152, 7, v76
	s_addc_u32 s23, s1, s37
	v_readlane_b32 s17, v254, 33
	v_lshlrev_b32_e32 v100, 7, v77
	v_lshlrev_b32_e32 v105, 4, v76
	v_lshl_add_u64 v[86:87], s[8:9], 0, v[0:1]
	v_lshl_add_u64 v[88:89], s[22:23], 0, v[152:153]
	v_add_u32_e32 v106, v7, v13
	v_add_u32_e32 v107, s6, v9
	v_add_u32_e32 v108, s6, v10
	v_add_u32_e32 v109, v12, v11
	v_add_u32_e32 v110, v8, v6
	s_mov_b32 s1, s17
	v_readlane_b32 s14, v252, 43
	v_readlane_b32 s15, v252, 44
	v_readlane_b32 s16, v252, 45
	v_readlane_b32 s18, v252, 47
	v_readlane_b32 s19, v252, 48
	s_branch .LBB0_323

.LBB0_328:
	s_setprio 0
	v_readlane_b32 s4, v252, 0
	s_or_b32 s1, s75, 1
	v_readlane_b32 s5, v252, 1
	s_cmp_lt_i32 s1, s5
	s_cselect_b64 s[10:11], -1, 0
	s_and_b64 s[4:5], s[60:61], s[10:11]
	s_andn2_b64 vcc, exec, s[4:5]
	v_readlane_b32 s4, v253, 20
	v_readlane_b32 s5, v253, 21
	s_nop 1
	v_cndmask_b32_e64 v0, 0, 1, s[4:5]
	v_cmp_ne_u32_e64 s[4:5], 1, v0
	s_nop 1
	v_writelane_b32 v255, s4, 21
	s_nop 1
	v_writelane_b32 v255, s5, 22
	s_cbranch_vccnz .LBB0_384
	v_readlane_b32 s4, v255, 21
	v_readlane_b32 s5, v255, 22
	s_and_b64 vcc, exec, s[4:5]
	s_mov_b64 s[18:19], 0
	s_cbranch_vccnz .LBB0_331
	v_mbcnt_lo_u32_b32 v0, -1, 0
	v_mbcnt_hi_u32_b32 v0, -1, v0
	s_nop 0
	v_cmp_eq_u32_e32 vcc, 0, v0
	s_and_b64 s[18:19], vcc, exec
